# mlstm_out: serialized 64-step LDS column-sum loop replaced by 16-deep batched reads (same order)
# baseline (speedup 1.0000x reference)
; __device__ __forceinline__ float bf2f(unsigned short v) { return __uint_as_float((unsigned)v << 16); }
; __device__ __forceinline__ void mlstm_out(KA a, LAS unsigned char* lds, int tid, int lane_in, int wave) {
;     ...
;             if (tid < 128) { float s = 0.f;
; #pragma unroll 8
;                 for (int s_ = 0; s_ < 64; ++s_) s += bf2f((unsigned short)KWs[s_ * PQ + tid]);
;                 fv[F_N + tid] = g.decay * fv[F_N + tid] + s; }
.LBB0_590:
	s_or_b64 exec, exec, s[76:77]
	v_sub_f32_e32 v158, v216, v209
	v_mul_f32_e32 v158, 0x3fb8aa3b, v158
	v_exp_f32_e32 v158, v158
	v_cmp_gt_i32_e32 vcc, s86, v217
	s_and_saveexec_b64 s[76:77], vcc
	s_cbranch_execz .LBB0_594
	v_lshl_add_u32 v216, v219, 1, s95
	v_mov_b32_e32 v219, 0
	s_mov_b32 vcc_lo, 0
	s_waitcnt lgkmcnt(0)
	ds_read_u16 v224, v216
	ds_read_u16 v225, v216 offset:272
	ds_read_u16 v226, v216 offset:544
	ds_read_u16 v227, v216 offset:816
	ds_read_u16 v228, v216 offset:1088
	ds_read_u16 v229, v216 offset:1360
	ds_read_u16 v230, v216 offset:1632
	ds_read_u16 v231, v216 offset:1904
	ds_read_u16 v232, v216 offset:2176
	ds_read_u16 v233, v216 offset:2448
	ds_read_u16 v234, v216 offset:2720
	ds_read_u16 v235, v216 offset:2992
	ds_read_u16 v236, v216 offset:3264
	ds_read_u16 v237, v216 offset:3536
	ds_read_u16 v238, v216 offset:3808
	ds_read_u16 v239, v216 offset:4080
	s_waitcnt lgkmcnt(15)
	v_lshlrev_b32_e32 v224, 16, v224
	v_add_f32_e32 v219, v219, v224
	s_waitcnt lgkmcnt(14)
	v_lshlrev_b32_e32 v225, 16, v225
	v_add_f32_e32 v219, v219, v225
	s_waitcnt lgkmcnt(13)
	v_lshlrev_b32_e32 v226, 16, v226
	v_add_f32_e32 v219, v219, v226
	s_waitcnt lgkmcnt(12)
	v_lshlrev_b32_e32 v227, 16, v227
	v_add_f32_e32 v219, v219, v227
	s_waitcnt lgkmcnt(11)
	v_lshlrev_b32_e32 v228, 16, v228
	v_add_f32_e32 v219, v219, v228
	s_waitcnt lgkmcnt(10)
	v_lshlrev_b32_e32 v229, 16, v229
	v_add_f32_e32 v219, v219, v229
	s_waitcnt lgkmcnt(9)
	v_lshlrev_b32_e32 v230, 16, v230
	v_add_f32_e32 v219, v219, v230
	s_waitcnt lgkmcnt(8)
	v_lshlrev_b32_e32 v231, 16, v231
	v_add_f32_e32 v219, v219, v231
	s_waitcnt lgkmcnt(7)
	v_lshlrev_b32_e32 v232, 16, v232
	v_add_f32_e32 v219, v219, v232
	s_waitcnt lgkmcnt(6)
	v_lshlrev_b32_e32 v233, 16, v233
	v_add_f32_e32 v219, v219, v233
	s_waitcnt lgkmcnt(5)
	v_lshlrev_b32_e32 v234, 16, v234
	v_add_f32_e32 v219, v219, v234
	s_waitcnt lgkmcnt(4)
	v_lshlrev_b32_e32 v235, 16, v235
	v_add_f32_e32 v219, v219, v235
	s_waitcnt lgkmcnt(3)
	v_lshlrev_b32_e32 v236, 16, v236
	v_add_f32_e32 v219, v219, v236
	s_waitcnt lgkmcnt(2)
	v_lshlrev_b32_e32 v237, 16, v237
	v_add_f32_e32 v219, v219, v237
	s_waitcnt lgkmcnt(1)
	v_lshlrev_b32_e32 v238, 16, v238
	v_add_f32_e32 v219, v219, v238
	s_waitcnt lgkmcnt(0)
	v_lshlrev_b32_e32 v239, 16, v239
	v_add_f32_e32 v219, v219, v239
	ds_read_u16 v224, v216 offset:4352
	ds_read_u16 v225, v216 offset:4624
	ds_read_u16 v226, v216 offset:4896
	ds_read_u16 v227, v216 offset:5168
	ds_read_u16 v228, v216 offset:5440
	ds_read_u16 v229, v216 offset:5712
	ds_read_u16 v230, v216 offset:5984
	ds_read_u16 v231, v216 offset:6256
	ds_read_u16 v232, v216 offset:6528
	ds_read_u16 v233, v216 offset:6800
	ds_read_u16 v234, v216 offset:7072
	ds_read_u16 v235, v216 offset:7344
	ds_read_u16 v236, v216 offset:7616
	ds_read_u16 v237, v216 offset:7888
	ds_read_u16 v238, v216 offset:8160
	ds_read_u16 v239, v216 offset:8432
	s_waitcnt lgkmcnt(15)
	v_lshlrev_b32_e32 v224, 16, v224
	v_add_f32_e32 v219, v219, v224
	s_waitcnt lgkmcnt(14)
	v_lshlrev_b32_e32 v225, 16, v225
	v_add_f32_e32 v219, v219, v225
	s_waitcnt lgkmcnt(13)
	v_lshlrev_b32_e32 v226, 16, v226
	v_add_f32_e32 v219, v219, v226
	s_waitcnt lgkmcnt(12)
	v_lshlrev_b32_e32 v227, 16, v227
	v_add_f32_e32 v219, v219, v227
	s_waitcnt lgkmcnt(11)
	v_lshlrev_b32_e32 v228, 16, v228
	v_add_f32_e32 v219, v219, v228
	s_waitcnt lgkmcnt(10)
	v_lshlrev_b32_e32 v229, 16, v229
	v_add_f32_e32 v219, v219, v229
	s_waitcnt lgkmcnt(9)
	v_lshlrev_b32_e32 v230, 16, v230
	v_add_f32_e32 v219, v219, v230
	s_waitcnt lgkmcnt(8)
	v_lshlrev_b32_e32 v231, 16, v231
	v_add_f32_e32 v219, v219, v231
	s_waitcnt lgkmcnt(7)
	v_lshlrev_b32_e32 v232, 16, v232
	v_add_f32_e32 v219, v219, v232
	s_waitcnt lgkmcnt(6)
	v_lshlrev_b32_e32 v233, 16, v233
	v_add_f32_e32 v219, v219, v233
	s_waitcnt lgkmcnt(5)
	v_lshlrev_b32_e32 v234, 16, v234
	v_add_f32_e32 v219, v219, v234
	s_waitcnt lgkmcnt(4)
	v_lshlrev_b32_e32 v235, 16, v235
	v_add_f32_e32 v219, v219, v235
	s_waitcnt lgkmcnt(3)
	v_lshlrev_b32_e32 v236, 16, v236
	v_add_f32_e32 v219, v219, v236
	s_waitcnt lgkmcnt(2)
	v_lshlrev_b32_e32 v237, 16, v237
	v_add_f32_e32 v219, v219, v237
	s_waitcnt lgkmcnt(1)
	v_lshlrev_b32_e32 v238, 16, v238
	v_add_f32_e32 v219, v219, v238
	s_waitcnt lgkmcnt(0)
; __device__ __forceinline__ float bf2f(unsigned short v) { return __uint_as_float((unsigned)v << 16); }
; __device__ __forceinline__ void mlstm_out(KA a, LAS unsigned char* lds, int tid, int lane_in, int wave) {
;     ...
;             if (tid < 128) { float s = 0.f;
; #pragma unroll 8
;                 for (int s_ = 0; s_ < 64; ++s_) s += bf2f((unsigned short)KWs[s_ * PQ + tid]);
;                 fv[F_N + tid] = g.decay * fv[F_N + tid] + s; }
	v_lshlrev_b32_e32 v239, 16, v239
	v_add_f32_e32 v219, v219, v239
	ds_read_u16 v224, v216 offset:8704
	ds_read_u16 v225, v216 offset:8976
	ds_read_u16 v226, v216 offset:9248
	ds_read_u16 v227, v216 offset:9520
	ds_read_u16 v228, v216 offset:9792
	ds_read_u16 v229, v216 offset:10064
	ds_read_u16 v230, v216 offset:10336
	ds_read_u16 v231, v216 offset:10608
	ds_read_u16 v232, v216 offset:10880
	ds_read_u16 v233, v216 offset:11152
	ds_read_u16 v234, v216 offset:11424
	ds_read_u16 v235, v216 offset:11696
	ds_read_u16 v236, v216 offset:11968
	ds_read_u16 v237, v216 offset:12240
	ds_read_u16 v238, v216 offset:12512
	ds_read_u16 v239, v216 offset:12784
	s_waitcnt lgkmcnt(15)
	v_lshlrev_b32_e32 v224, 16, v224
	v_add_f32_e32 v219, v219, v224
	s_waitcnt lgkmcnt(14)
	v_lshlrev_b32_e32 v225, 16, v225
	v_add_f32_e32 v219, v219, v225
	s_waitcnt lgkmcnt(13)
	v_lshlrev_b32_e32 v226, 16, v226
	v_add_f32_e32 v219, v219, v226
	s_waitcnt lgkmcnt(12)
	v_lshlrev_b32_e32 v227, 16, v227
	v_add_f32_e32 v219, v219, v227
	s_waitcnt lgkmcnt(11)
	v_lshlrev_b32_e32 v228, 16, v228
	v_add_f32_e32 v219, v219, v228
	s_waitcnt lgkmcnt(10)
	v_lshlrev_b32_e32 v229, 16, v229
	v_add_f32_e32 v219, v219, v229
	s_waitcnt lgkmcnt(9)
	v_lshlrev_b32_e32 v230, 16, v230
	v_add_f32_e32 v219, v219, v230
	s_waitcnt lgkmcnt(8)
	v_lshlrev_b32_e32 v231, 16, v231
	v_add_f32_e32 v219, v219, v231
	s_waitcnt lgkmcnt(7)
	v_lshlrev_b32_e32 v232, 16, v232
	v_add_f32_e32 v219, v219, v232
	s_waitcnt lgkmcnt(6)
	v_lshlrev_b32_e32 v233, 16, v233
	v_add_f32_e32 v219, v219, v233
	s_waitcnt lgkmcnt(5)
	v_lshlrev_b32_e32 v234, 16, v234
	v_add_f32_e32 v219, v219, v234
	s_waitcnt lgkmcnt(4)
	v_lshlrev_b32_e32 v235, 16, v235
	v_add_f32_e32 v219, v219, v235
	s_waitcnt lgkmcnt(3)
	v_lshlrev_b32_e32 v236, 16, v236
	v_add_f32_e32 v219, v219, v236
	s_waitcnt lgkmcnt(2)
	v_lshlrev_b32_e32 v237, 16, v237
	v_add_f32_e32 v219, v219, v237
	s_waitcnt lgkmcnt(1)
	v_lshlrev_b32_e32 v238, 16, v238
	v_add_f32_e32 v219, v219, v238
	s_waitcnt lgkmcnt(0)
	v_lshlrev_b32_e32 v239, 16, v239
	v_add_f32_e32 v219, v219, v239
	ds_read_u16 v224, v216 offset:13056
	ds_read_u16 v225, v216 offset:13328
	ds_read_u16 v226, v216 offset:13600
	ds_read_u16 v227, v216 offset:13872
	ds_read_u16 v228, v216 offset:14144
	ds_read_u16 v229, v216 offset:14416
	ds_read_u16 v230, v216 offset:14688
	ds_read_u16 v231, v216 offset:14960
	ds_read_u16 v232, v216 offset:15232
	ds_read_u16 v233, v216 offset:15504
	ds_read_u16 v234, v216 offset:15776
	ds_read_u16 v235, v216 offset:16048
	ds_read_u16 v236, v216 offset:16320
	ds_read_u16 v237, v216 offset:16592
	ds_read_u16 v238, v216 offset:16864
	ds_read_u16 v239, v216 offset:17136
	s_waitcnt lgkmcnt(15)
	v_lshlrev_b32_e32 v224, 16, v224
	v_add_f32_e32 v219, v219, v224
	s_waitcnt lgkmcnt(14)
	v_lshlrev_b32_e32 v225, 16, v225
	v_add_f32_e32 v219, v219, v225
	s_waitcnt lgkmcnt(13)
	v_lshlrev_b32_e32 v226, 16, v226
	v_add_f32_e32 v219, v219, v226
	s_waitcnt lgkmcnt(12)
	v_lshlrev_b32_e32 v227, 16, v227
	v_add_f32_e32 v219, v219, v227
	s_waitcnt lgkmcnt(11)
	v_lshlrev_b32_e32 v228, 16, v228
	v_add_f32_e32 v219, v219, v228
	s_waitcnt lgkmcnt(10)
	v_lshlrev_b32_e32 v229, 16, v229
	v_add_f32_e32 v219, v219, v229
	s_waitcnt lgkmcnt(9)
	v_lshlrev_b32_e32 v230, 16, v230
	v_add_f32_e32 v219, v219, v230
	s_waitcnt lgkmcnt(8)
	v_lshlrev_b32_e32 v231, 16, v231
	v_add_f32_e32 v219, v219, v231
	s_waitcnt lgkmcnt(7)
	v_lshlrev_b32_e32 v232, 16, v232
	v_add_f32_e32 v219, v219, v232
	s_waitcnt lgkmcnt(6)
	v_lshlrev_b32_e32 v233, 16, v233
	v_add_f32_e32 v219, v219, v233
	s_waitcnt lgkmcnt(5)
	v_lshlrev_b32_e32 v234, 16, v234
	v_add_f32_e32 v219, v219, v234
	s_waitcnt lgkmcnt(4)
	v_lshlrev_b32_e32 v235, 16, v235
	v_add_f32_e32 v219, v219, v235
	s_waitcnt lgkmcnt(3)
	v_lshlrev_b32_e32 v236, 16, v236
	v_add_f32_e32 v219, v219, v236
	s_waitcnt lgkmcnt(2)
	v_lshlrev_b32_e32 v237, 16, v237
	v_add_f32_e32 v219, v219, v237
	s_waitcnt lgkmcnt(1)
	v_lshlrev_b32_e32 v238, 16, v238
	v_add_f32_e32 v219, v219, v238
	s_waitcnt lgkmcnt(0)
	v_lshlrev_b32_e32 v239, 16, v239
	v_add_f32_e32 v219, v219, v239
	v_lshl_add_u32 v216, v217, 2, s89
	ds_read_b32 v217, v216 offset:1024
	s_waitcnt lgkmcnt(0)
	v_fmac_f32_e32 v219, v158, v217
	ds_write_b32 v216, v219 offset:1024
